# gla_pass3: the once-read f32 z row loads marked nt (streaming), leaving L2 to the re-read ofwd and state data
# speedup vs baseline: 1.0113x; 1.0018x over previous
; __device__ __forceinline__ void gla_pass3(const Ctx& cx, const Params& p, int l, int item, float* ldsf, int lane) {
;     ...
;     const bfu* Sp = reinterpret_cast<const bfu*>(p.ws + OFF_GU) + ((size_t)(chain * 36 + n) << 12);
;     const float lb = (m == 0) ? lower_bound(p, l, dir, hc) : 0.f;
;     const int cfoff = (m == 0) ? (dir ? 1024 : 512) : 3072;
;     f32x4 T[4][4];
; #pragma unroll
;     for (int db = 0; db < 4; ++db)
; #pragma unroll
;       for (int vb = 0; vb < 4; ++vb) {
;         const u32x2 sv = *reinterpret_cast<const u32x2*>(Sp + (16 * vb + c) * 64 + 16 * db + 4 * g);
;         T[db][vb] = (f32x4){__uint_as_float(sv.x << 16), __uint_as_float(sv.x & 0xffff0000u), __uint_as_float(sv.y << 16), __uint_as_float(sv.y & 0xffff0000u)};
;       }
;     float r0[16], r1[16], r2[16];
; #pragma unroll
;     for (int i = 0; i < 16; ++i) {
;       int tok = dir ? 63 - i : i;
;       const float* zr = z + (size_t)(rowbase + tok) * INW;
;       r0[i] = zr[cfoff + hc];
;       r1[i] = zr[cqoff + hc];
;       r2[i] = zr[cvoff + hc];
;     }
.LBB0_127:
	v_cndmask_b32_e64 v4, v154, v146, s[0:1]
	v_or_b32_e32 v5, s2, v155
	v_mad_u64_u32 v[4:5], s[6:7], v5, 36, v[4:5]
	v_ashrrev_i32_e32 v5, 31, v4
	s_xor_b64 s[48:49], s[0:1], -1
	v_lshlrev_b64 v[4:5], 13, v[4:5]
	s_and_b64 s[6:7], s[0:1], exec
	v_lshl_add_u64 v[4:5], v[108:109], 0, v[4:5]
	v_mov_b32_e32 v115, v18
	v_mov_b32_e32 v113, v18
	v_lshl_add_u64 v[6:7], v[4:5], 0, v[114:115]
	v_mov_b32_e32 v117, v18
	v_lshl_add_u64 v[12:13], v[4:5], 0, 32
	s_mov_b64 s[6:7], 0x60
	s_movk_i32 s3, 0x400
	v_lshl_add_u64 v[8:9], v[4:5], 0, v[112:113]
	v_lshl_add_u64 v[10:11], v[4:5], 0, v[116:117]
	v_lshl_add_u64 v[16:17], v[12:13], 0, v[114:115]
	v_lshl_add_u64 v[12:13], v[12:13], 0, v[116:117]
	global_load_dwordx2 v[14:15], v[6:7], off
	global_load_dwordx2 v[22:23], v[10:11], off
	global_load_dwordx2 v[34:35], v[16:17], off
	global_load_dwordx2 v[38:39], v[12:13], off
	v_lshl_add_u64 v[6:7], v[4:5], 0, 64
	v_lshl_add_u64 v[4:5], v[4:5], 0, s[6:7]
	s_cselect_b32 s3, 0x200, s3
	v_lshl_add_u64 v[12:13], v[6:7], 0, v[114:115]
	v_lshl_add_u64 v[16:17], v[6:7], 0, v[116:117]
	global_load_dwordx2 v[6:7], v[8:9], off
	global_load_dwordx2 v[26:27], v[8:9], off offset:32
	global_load_dwordx2 v[42:43], v[8:9], off offset:64
	global_load_dwordx2 v[58:59], v[8:9], off offset:96
	global_load_dwordx2 v[10:11], v[8:9], off offset:2048
	global_load_dwordx2 v[30:31], v[8:9], off offset:2080
	global_load_dwordx2 v[46:47], v[8:9], off offset:2112
	global_load_dwordx2 v[62:63], v[8:9], off offset:2144
	v_lshl_add_u64 v[8:9], v[4:5], 0, v[114:115]
	v_lshl_add_u64 v[4:5], v[4:5], 0, v[116:117]
	global_load_dwordx2 v[50:51], v[12:13], off
	global_load_dwordx2 v[54:55], v[16:17], off
	global_load_dwordx2 v[66:67], v[8:9], off
	global_load_dwordx2 v[70:71], v[4:5], off
	v_mov_b32_e32 v4, s3
	v_cndmask_b32_e64 v4, v185, v4, s[46:47]
	s_cselect_b32 s3, 0, 63
	v_or_b32_e32 v16, v4, v119
	v_or_b32_e32 v4, s3, v147
	s_cselect_b32 s3, 1, 62
	v_or_b32_e32 v17, s3, v147
	s_cselect_b32 s3, 2, 61
	v_mul_lo_u32 v4, v4, s25
	v_mul_lo_u32 v24, v17, s25
	v_or_b32_e32 v17, s3, v147
	v_ashrrev_i32_e32 v5, 31, v4
	v_mul_lo_u32 v36, v17, s25
	v_lshl_add_u64 v[4:5], v[4:5], 2, s[22:23]
	v_lshlrev_b32_e32 v8, 2, v16
	v_mov_b32_e32 v9, v18
	v_ashrrev_i32_e32 v25, 31, v24
	v_ashrrev_i32_e32 v37, 31, v36
	v_lshl_add_u64 v[12:13], v[4:5], 0, v[8:9]
	v_lshlrev_b32_e32 v130, 2, v124
	v_mov_b32_e32 v131, v18
	v_lshlrev_b32_e32 v132, 2, v126
	v_mov_b32_e32 v133, v18
	v_lshl_add_u64 v[24:25], v[24:25], 2, s[22:23]
	v_lshl_add_u64 v[36:37], v[36:37], 2, s[22:23]
	s_cselect_b32 s3, 3, 60
	v_lshl_add_u64 v[20:21], v[4:5], 0, v[130:131]
	v_lshl_add_u64 v[4:5], v[4:5], 0, v[132:133]
	v_lshl_add_u64 v[28:29], v[24:25], 0, v[8:9]
	v_lshl_add_u64 v[32:33], v[24:25], 0, v[130:131]
	v_lshl_add_u64 v[24:25], v[24:25], 0, v[132:133]
	v_lshl_add_u64 v[40:41], v[36:37], 0, v[8:9]
	v_lshl_add_u64 v[44:45], v[36:37], 0, v[130:131]
	global_load_dword v117, v[12:13], off nt
	global_load_dword v111, v[20:21], off nt
	global_load_dword v123, v[4:5], off nt
	global_load_dword v157, v[28:29], off nt
	global_load_dword v113, v[32:33], off nt
	global_load_dword v156, v[24:25], off nt
	global_load_dword v158, v[40:41], off nt
	global_load_dword v115, v[44:45], off nt
	v_or_b32_e32 v12, s3, v147
	s_cselect_b32 s3, 4, 59
	v_or_b32_e32 v17, s3, v147
	s_cselect_b32 s3, 5, 58
	v_mul_lo_u32 v12, v12, s25
	v_mul_lo_u32 v28, v17, s25
	v_or_b32_e32 v17, s3, v147
	v_ashrrev_i32_e32 v13, 31, v12
	v_mul_lo_u32 v40, v17, s25
	v_lshl_add_u64 v[12:13], v[12:13], 2, s[22:23]
	v_ashrrev_i32_e32 v29, 31, v28
	v_ashrrev_i32_e32 v41, 31, v40
	s_cselect_b32 s3, 6, 57
	v_lshl_add_u64 v[4:5], v[36:37], 0, v[132:133]
	v_lshl_add_u64 v[20:21], v[12:13], 0, v[8:9]
	v_lshl_add_u64 v[28:29], v[28:29], 2, s[22:23]
	v_lshl_add_u64 v[40:41], v[40:41], 2, s[22:23]
	v_or_b32_e32 v17, s3, v147
	s_cselect_b32 s3, 7, 56
	v_lshl_add_u64 v[24:25], v[12:13], 0, v[130:131]
	v_lshl_add_u64 v[12:13], v[12:13], 0, v[132:133]
	v_lshl_add_u64 v[32:33], v[28:29], 0, v[8:9]
	v_lshl_add_u64 v[36:37], v[28:29], 0, v[130:131]
	v_lshl_add_u64 v[28:29], v[28:29], 0, v[132:133]
	v_lshl_add_u64 v[44:45], v[40:41], 0, v[8:9]
	global_load_dword v161, v[4:5], off nt
	global_load_dword v164, v[20:21], off nt
	global_load_dword v159, v[24:25], off nt
	global_load_dword v162, v[12:13], off nt
	global_load_dword v165, v[32:33], off nt
	global_load_dword v160, v[36:37], off nt
	global_load_dword v163, v[28:29], off nt
	global_load_dword v166, v[44:45], off nt
	v_mul_lo_u32 v20, v17, s25
	v_or_b32_e32 v17, s3, v147
	v_mul_lo_u32 v32, v17, s25
	v_ashrrev_i32_e32 v21, 31, v20
	v_ashrrev_i32_e32 v33, 31, v32
	v_lshl_add_u64 v[4:5], v[40:41], 0, v[130:131]
	v_lshl_add_u64 v[20:21], v[20:21], 2, s[22:23]
	v_lshl_add_u64 v[32:33], v[32:33], 2, s[22:23]
	s_cselect_b32 s3, 8, 55
	v_lshl_add_u64 v[12:13], v[40:41], 0, v[132:133]
	v_lshl_add_u64 v[24:25], v[20:21], 0, v[8:9]
	v_lshl_add_u64 v[28:29], v[20:21], 0, v[130:131]
	v_lshl_add_u64 v[20:21], v[20:21], 0, v[132:133]
	v_lshl_add_u64 v[36:37], v[32:33], 0, v[8:9]
	v_lshl_add_u64 v[40:41], v[32:33], 0, v[130:131]
	v_lshl_add_u64 v[32:33], v[32:33], 0, v[132:133]
	global_load_dword v167, v[4:5], off nt
	global_load_dword v170, v[12:13], off nt
	global_load_dword v173, v[24:25], off nt
	global_load_dword v168, v[28:29], off nt
	global_load_dword v171, v[20:21], off nt
	global_load_dword v203, v[36:37], off nt
	global_load_dword v169, v[40:41], off nt
	global_load_dword v172, v[32:33], off nt
	v_or_b32_e32 v4, s3, v147
	s_cselect_b32 s3, 9, 54
	v_or_b32_e32 v17, s3, v147
	s_cselect_b32 s3, 10, 53
	v_mul_lo_u32 v4, v4, s25
; __device__ __forceinline__ void gla_pass3(const Ctx& cx, const Params& p, int l, int item, float* ldsf, int lane) {
;     ...
;       for (int vb = 0; vb < 4; ++vb) {
;         const u32x2 sv = *reinterpret_cast<const u32x2*>(Sp + (16 * vb + c) * 64 + 16 * db + 4 * g);
;         T[db][vb] = (f32x4){__uint_as_float(sv.x << 16), __uint_as_float(sv.x & 0xffff0000u), __uint_as_float(sv.y << 16), __uint_as_float(sv.y & 0xffff0000u)};
;       }
;     float r0[16], r1[16], r2[16];
; #pragma unroll
;     for (int i = 0; i < 16; ++i) {
;       int tok = dir ? 63 - i : i;
;       const float* zr = z + (size_t)(rowbase + tok) * INW;
;       r0[i] = zr[cfoff + hc];
;       r1[i] = zr[cqoff + hc];
;       r2[i] = zr[cvoff + hc];
;     }
	v_mul_lo_u32 v24, v17, s25
	v_or_b32_e32 v17, s3, v147
	v_ashrrev_i32_e32 v5, 31, v4
	v_mul_lo_u32 v36, v17, s25
	v_lshl_add_u64 v[4:5], v[4:5], 2, s[22:23]
	v_ashrrev_i32_e32 v25, 31, v24
	v_ashrrev_i32_e32 v37, 31, v36
	v_lshl_add_u64 v[12:13], v[4:5], 0, v[8:9]
	v_lshl_add_u64 v[24:25], v[24:25], 2, s[22:23]
	v_lshl_add_u64 v[36:37], v[36:37], 2, s[22:23]
	s_cselect_b32 s3, 11, 52
	v_lshl_add_u64 v[20:21], v[4:5], 0, v[130:131]
	v_lshl_add_u64 v[4:5], v[4:5], 0, v[132:133]
	v_lshl_add_u64 v[28:29], v[24:25], 0, v[8:9]
	v_lshl_add_u64 v[32:33], v[24:25], 0, v[130:131]
	v_lshl_add_u64 v[24:25], v[24:25], 0, v[132:133]
	v_lshl_add_u64 v[40:41], v[36:37], 0, v[8:9]
	v_lshl_add_u64 v[44:45], v[36:37], 0, v[130:131]
	global_load_dword v209, v[12:13], off nt
	global_load_dword v204, v[20:21], off nt
	global_load_dword v207, v[4:5], off nt
	global_load_dword v210, v[28:29], off nt
	global_load_dword v205, v[32:33], off nt
	global_load_dword v208, v[24:25], off nt
	global_load_dword v211, v[40:41], off nt
	global_load_dword v206, v[44:45], off nt
	v_or_b32_e32 v12, s3, v147
	s_cselect_b32 s3, 12, 51
	v_or_b32_e32 v17, s3, v147
	s_cselect_b32 s3, 13, 50
	v_mul_lo_u32 v12, v12, s25
	v_mul_lo_u32 v28, v17, s25
	v_or_b32_e32 v17, s3, v147
	v_ashrrev_i32_e32 v13, 31, v12
	v_mul_lo_u32 v40, v17, s25
	v_lshl_add_u64 v[12:13], v[12:13], 2, s[22:23]
	v_ashrrev_i32_e32 v29, 31, v28
	v_ashrrev_i32_e32 v41, 31, v40
	s_cselect_b32 s3, 14, 49
	v_lshl_add_u64 v[4:5], v[36:37], 0, v[132:133]
	v_lshl_add_u64 v[20:21], v[12:13], 0, v[8:9]
	v_lshl_add_u64 v[28:29], v[28:29], 2, s[22:23]
	v_lshl_add_u64 v[40:41], v[40:41], 2, s[22:23]
	v_or_b32_e32 v17, s3, v147
	s_cselect_b32 s3, 15, 48
	v_lshl_add_u64 v[24:25], v[12:13], 0, v[130:131]
	v_lshl_add_u64 v[12:13], v[12:13], 0, v[132:133]
	v_lshl_add_u64 v[32:33], v[28:29], 0, v[8:9]
	v_lshl_add_u64 v[36:37], v[28:29], 0, v[130:131]
	v_lshl_add_u64 v[28:29], v[28:29], 0, v[132:133]
	v_lshl_add_u64 v[44:45], v[40:41], 0, v[8:9]
	global_load_dword v214, v[4:5], off nt
	global_load_dword v220, v[20:21], off nt
	global_load_dword v212, v[24:25], off nt
	global_load_dword v215, v[12:13], off nt
	global_load_dword v221, v[32:33], off nt
	global_load_dword v213, v[36:37], off nt
	global_load_dword v216, v[28:29], off nt
	global_load_dword v222, v[44:45], off nt
	v_mul_lo_u32 v20, v17, s25
	v_or_b32_e32 v17, s3, v147
	v_mul_lo_u32 v32, v17, s25
	v_ashrrev_i32_e32 v21, 31, v20
	v_ashrrev_i32_e32 v33, 31, v32
	v_lshl_add_u64 v[4:5], v[40:41], 0, v[130:131]
	v_lshl_add_u64 v[20:21], v[20:21], 2, s[22:23]
	v_lshl_add_u64 v[32:33], v[32:33], 2, s[22:23]
	v_lshl_add_u64 v[12:13], v[40:41], 0, v[132:133]
	v_lshl_add_u64 v[24:25], v[20:21], 0, v[8:9]
	v_lshl_add_u64 v[28:29], v[20:21], 0, v[130:131]
	v_lshl_add_u64 v[20:21], v[20:21], 0, v[132:133]
	v_lshl_add_u64 v[8:9], v[32:33], 0, v[8:9]
	v_lshl_add_u64 v[36:37], v[32:33], 0, v[130:131]
	v_lshl_add_u64 v[32:33], v[32:33], 0, v[132:133]
	global_load_dword v217, v[4:5], off nt
	global_load_dword v223, v[12:13], off nt
	global_load_dword v226, v[24:25], off nt
	global_load_dword v218, v[28:29], off nt
	global_load_dword v224, v[20:21], off nt
	global_load_dword v227, v[8:9], off nt
	global_load_dword v219, v[36:37], off nt
	global_load_dword v225, v[32:33], off nt
	s_waitcnt vmcnt(59)
	v_lshlrev_b32_e32 v4, 16, v6
	v_and_b32_e32 v5, 0xffff0000, v6
	v_lshlrev_b32_e32 v6, 16, v7
	v_and_b32_e32 v7, 0xffff0000, v7
	s_waitcnt vmcnt(55)
	v_lshlrev_b32_e32 v8, 16, v10
	v_and_b32_e32 v9, 0xffff0000, v10
	v_lshlrev_b32_e32 v10, 16, v11
	v_and_b32_e32 v11, 0xffff0000, v11
	v_lshlrev_b32_e32 v12, 16, v14
	v_and_b32_e32 v13, 0xffff0000, v14
	v_lshlrev_b32_e32 v14, 16, v15
	v_and_b32_e32 v15, 0xffff0000, v15
	v_lshlrev_b32_e32 v20, 16, v22
	v_and_b32_e32 v21, 0xffff0000, v22
	v_lshlrev_b32_e32 v22, 16, v23
	v_and_b32_e32 v23, 0xffff0000, v23
	v_lshlrev_b32_e32 v24, 16, v26
	v_and_b32_e32 v25, 0xffff0000, v26
	v_lshlrev_b32_e32 v26, 16, v27
	v_and_b32_e32 v27, 0xffff0000, v27
	s_waitcnt vmcnt(54)
	v_lshlrev_b32_e32 v28, 16, v30
	v_and_b32_e32 v29, 0xffff0000, v30
	v_lshlrev_b32_e32 v30, 16, v31
	v_and_b32_e32 v31, 0xffff0000, v31
	v_lshlrev_b32_e32 v32, 16, v34
	v_and_b32_e32 v33, 0xffff0000, v34
	v_lshlrev_b32_e32 v34, 16, v35
	v_and_b32_e32 v35, 0xffff0000, v35
	v_lshlrev_b32_e32 v36, 16, v38
	v_and_b32_e32 v37, 0xffff0000, v38
	v_lshlrev_b32_e32 v38, 16, v39
	v_and_b32_e32 v39, 0xffff0000, v39
	v_lshlrev_b32_e32 v40, 16, v42
	v_and_b32_e32 v41, 0xffff0000, v42
	v_lshlrev_b32_e32 v42, 16, v43
	v_and_b32_e32 v43, 0xffff0000, v43
	s_waitcnt vmcnt(53)
	v_lshlrev_b32_e32 v44, 16, v46
	v_and_b32_e32 v45, 0xffff0000, v46
	v_lshlrev_b32_e32 v46, 16, v47
	v_and_b32_e32 v47, 0xffff0000, v47
	s_waitcnt vmcnt(51)
	v_lshlrev_b32_e32 v48, 16, v50
	v_and_b32_e32 v49, 0xffff0000, v50
	v_lshlrev_b32_e32 v50, 16, v51
	v_and_b32_e32 v51, 0xffff0000, v51
	s_waitcnt vmcnt(50)
	v_lshlrev_b32_e32 v52, 16, v54
	v_and_b32_e32 v53, 0xffff0000, v54
	v_lshlrev_b32_e32 v54, 16, v55
	v_and_b32_e32 v55, 0xffff0000, v55
	v_lshlrev_b32_e32 v56, 16, v58
	v_and_b32_e32 v57, 0xffff0000, v58
	v_lshlrev_b32_e32 v58, 16, v59
	v_and_b32_e32 v59, 0xffff0000, v59
	v_lshlrev_b32_e32 v60, 16, v62
	v_and_b32_e32 v61, 0xffff0000, v62
	v_lshlrev_b32_e32 v62, 16, v63
	v_and_b32_e32 v63, 0xffff0000, v63
	s_waitcnt vmcnt(49)
	v_lshlrev_b32_e32 v64, 16, v66
	v_and_b32_e32 v65, 0xffff0000, v66
	v_lshlrev_b32_e32 v66, 16, v67
	v_and_b32_e32 v67, 0xffff0000, v67
	s_waitcnt vmcnt(48)
	v_lshlrev_b32_e32 v68, 16, v70
	v_and_b32_e32 v69, 0xffff0000, v70
	v_lshlrev_b32_e32 v70, 16, v71
	v_and_b32_e32 v71, 0xffff0000, v71
	s_mul_i32 s92, s2, 0x2400
	s_mov_b32 s6, 32
	v_lshlrev_b32_e32 v134, 2, v16
	s_mov_b32 s10, 0
	s_branch .LBB0_130

; __device__ __forceinline__ bfu f2bf_hw(float x) { return (bfu)(pack2(x, x) & 0xffffu); }
; __device__ __forceinline__ void gla_pass3(const Ctx& cx, const Params& p, int l, int item, float* ldsf, int lane) {
;     ...
; #pragma unroll
;         for (int i = 0; i < 16; ++i) {
;           float f, k, q;
;           if (m == 0) { f = r0[i]; k = 1.f - f; q = r1[i]; }
;           else { f = fconst; k = r0[i]; q = r1[i]; }
;           e = fmaxf(e * f, 1e-26f);
;           const float ie = __builtin_amdgcn_rcpf(e);
;           kt[i] = k * ie;
;           Qs[i * 68 + lane] = f2bf_hw(q * e);
;           Ks[i * 68 + lane] = f2bf_hw(kt[i]);
;         }
.LBB0_130:
	s_waitcnt vmcnt(47)
	v_cndmask_b32_e64 v16, v153, v117, s[46:47]
	v_max_f32_e32 v16, v16, v16
	v_max_f32_e32 v16, 0x14461206, v16
	v_rcp_f32_e32 v17, v16
	v_sub_f32_e32 v19, 1.0, v117
	v_cndmask_b32_e64 v19, v117, v19, s[46:47]
	s_waitcnt vmcnt(46)
	v_mul_f32_e32 v72, v111, v16
	v_mul_f32_e32 v17, v19, v17
	v_cvt_pk_bf16_f32 v19, v72, s0
	s_waitcnt vmcnt(44)
	v_cndmask_b32_e64 v72, v153, v157, s[46:47]
	v_mul_f32_e32 v16, v16, v72
	v_max_f32_e32 v16, 0x14461206, v16
	v_rcp_f32_e32 v72, v16
	ds_write_b16 v107, v19
	v_cvt_pk_bf16_f32 v19, v17, s0
	ds_write_b16 v107, v19 offset:2176
	v_sub_f32_e32 v19, 1.0, v157
	v_cndmask_b32_e64 v19, v157, v19, s[46:47]
	s_waitcnt vmcnt(41)
	v_cndmask_b32_e64 v73, v153, v158, s[46:47]
	v_mul_f32_e32 v19, v19, v72
	v_mul_f32_e32 v72, v113, v16
	v_mul_f32_e32 v16, v73, v16
	v_max_f32_e32 v16, 0x14461206, v16
	v_cvt_pk_bf16_f32 v72, v72, s0
	v_rcp_f32_e32 v73, v16
	ds_write_b16 v107, v72 offset:136
	v_cvt_pk_bf16_f32 v72, v19, s0
	ds_write_b16 v107, v72 offset:2312
	v_sub_f32_e32 v72, 1.0, v158
	v_cndmask_b32_e64 v72, v158, v72, s[46:47]
	s_waitcnt vmcnt(38)
	v_cndmask_b32_e64 v74, v153, v164, s[46:47]
	v_mul_f32_e32 v72, v72, v73
	v_mul_f32_e32 v73, v115, v16
	v_mul_f32_e32 v16, v74, v16
	v_max_f32_e32 v16, 0x14461206, v16
	v_cvt_pk_bf16_f32 v73, v73, s0
	v_rcp_f32_e32 v74, v16
	ds_write_b16 v107, v73 offset:272
	v_cvt_pk_bf16_f32 v73, v72, s0
	ds_write_b16 v107, v73 offset:2448
	v_sub_f32_e32 v73, 1.0, v164
	v_cndmask_b32_e64 v73, v164, v73, s[46:47]
	s_waitcnt vmcnt(35)
	v_cndmask_b32_e64 v75, v153, v165, s[46:47]
	v_mul_f32_e32 v73, v73, v74
	v_mul_f32_e32 v74, v159, v16
	v_mul_f32_e32 v16, v75, v16
	v_max_f32_e32 v16, 0x14461206, v16
	v_cvt_pk_bf16_f32 v74, v74, s0
	v_rcp_f32_e32 v75, v16
	ds_write_b16 v107, v74 offset:408
	v_cvt_pk_bf16_f32 v74, v73, s0
	ds_write_b16 v107, v74 offset:2584
	v_sub_f32_e32 v74, 1.0, v165
	v_cndmask_b32_e64 v74, v165, v74, s[46:47]
	s_waitcnt vmcnt(32)
	v_cndmask_b32_e64 v76, v153, v166, s[46:47]
	v_mul_f32_e32 v74, v74, v75
	v_mul_f32_e32 v75, v160, v16
	v_mul_f32_e32 v16, v76, v16
	v_max_f32_e32 v16, 0x14461206, v16
	v_cvt_pk_bf16_f32 v75, v75, s0
	v_rcp_f32_e32 v76, v16
	ds_write_b16 v107, v75 offset:544
	v_cvt_pk_bf16_f32 v75, v74, s0
	ds_write_b16 v107, v75 offset:2720
	v_sub_f32_e32 v75, 1.0, v166
	v_cndmask_b32_e64 v75, v166, v75, s[46:47]
	s_waitcnt vmcnt(29)
	v_cndmask_b32_e64 v77, v153, v173, s[46:47]
	v_mul_f32_e32 v75, v75, v76
	v_mul_f32_e32 v76, v167, v16
	v_mul_f32_e32 v16, v77, v16
	v_max_f32_e32 v16, 0x14461206, v16
	v_cvt_pk_bf16_f32 v76, v76, s0
	v_rcp_f32_e32 v77, v16
	ds_write_b16 v107, v76 offset:680
	v_cvt_pk_bf16_f32 v76, v75, s0
	ds_write_b16 v107, v76 offset:2856
	v_sub_f32_e32 v76, 1.0, v173
	v_cndmask_b32_e64 v76, v173, v76, s[46:47]
	s_waitcnt vmcnt(26)
	v_cndmask_b32_e64 v78, v153, v203, s[46:47]
	v_mul_f32_e32 v76, v76, v77
	v_mul_f32_e32 v77, v168, v16
	v_mul_f32_e32 v16, v78, v16
	v_max_f32_e32 v16, 0x14461206, v16
	v_cvt_pk_bf16_f32 v77, v77, s0
	v_rcp_f32_e32 v78, v16
	ds_write_b16 v107, v77 offset:816
	v_cvt_pk_bf16_f32 v77, v76, s0
	ds_write_b16 v107, v77 offset:2992
	v_sub_f32_e32 v77, 1.0, v203
	v_cndmask_b32_e64 v77, v203, v77, s[46:47]
	s_waitcnt vmcnt(23)
	v_cndmask_b32_e64 v79, v153, v209, s[46:47]
	v_mul_f32_e32 v77, v77, v78
	v_mul_f32_e32 v78, v169, v16
	v_mul_f32_e32 v16, v79, v16
	v_max_f32_e32 v16, 0x14461206, v16
	v_cvt_pk_bf16_f32 v78, v78, s0
	v_rcp_f32_e32 v79, v16
	ds_write_b16 v107, v78 offset:952
	v_cvt_pk_bf16_f32 v78, v77, s0
	ds_write_b16 v107, v78 offset:3128
	v_sub_f32_e32 v78, 1.0, v209
	v_cndmask_b32_e64 v78, v209, v78, s[46:47]
	s_waitcnt vmcnt(20)
	v_cndmask_b32_e64 v80, v153, v210, s[46:47]
	v_mul_f32_e32 v78, v78, v79
	v_mul_f32_e32 v79, v204, v16
	v_mul_f32_e32 v16, v80, v16
	v_max_f32_e32 v16, 0x14461206, v16
	v_cvt_pk_bf16_f32 v79, v79, s0
	v_rcp_f32_e32 v80, v16
	ds_write_b16 v107, v79 offset:1088
	v_cvt_pk_bf16_f32 v79, v78, s0
	ds_write_b16 v107, v79 offset:3264
	v_sub_f32_e32 v79, 1.0, v210
	v_cndmask_b32_e64 v79, v210, v79, s[46:47]
	s_waitcnt vmcnt(17)
	v_cndmask_b32_e64 v81, v153, v211, s[46:47]
	v_mul_f32_e32 v79, v79, v80
	v_mul_f32_e32 v80, v205, v16
	v_mul_f32_e32 v16, v81, v16
	v_max_f32_e32 v16, 0x14461206, v16
	v_cvt_pk_bf16_f32 v80, v80, s0
	v_rcp_f32_e32 v81, v16
	ds_write_b16 v107, v80 offset:1224
	v_cvt_pk_bf16_f32 v80, v79, s0
	ds_write_b16 v107, v80 offset:3400
	v_sub_f32_e32 v80, 1.0, v211
	v_cndmask_b32_e64 v80, v211, v80, s[46:47]
	s_waitcnt vmcnt(14)
	v_cndmask_b32_e64 v82, v153, v220, s[46:47]
	v_mul_f32_e32 v80, v80, v81
	v_mul_f32_e32 v81, v206, v16
	v_mul_f32_e32 v16, v82, v16
	v_max_f32_e32 v16, 0x14461206, v16
	v_cvt_pk_bf16_f32 v81, v81, s0
	v_rcp_f32_e32 v82, v16
	ds_write_b16 v107, v81 offset:1360
	v_cvt_pk_bf16_f32 v81, v80, s0
	ds_write_b16 v107, v81 offset:3536
	v_sub_f32_e32 v81, 1.0, v220
	v_cndmask_b32_e64 v81, v220, v81, s[46:47]
	s_waitcnt vmcnt(11)
	v_cndmask_b32_e64 v83, v153, v221, s[46:47]
	v_mul_f32_e32 v81, v81, v82
	v_mul_f32_e32 v82, v212, v16
	v_mul_f32_e32 v16, v83, v16
	v_max_f32_e32 v16, 0x14461206, v16
	v_cvt_pk_bf16_f32 v82, v82, s0
	v_rcp_f32_e32 v83, v16
	ds_write_b16 v107, v82 offset:1496
	v_cvt_pk_bf16_f32 v82, v81, s0
	ds_write_b16 v107, v82 offset:3672
	v_sub_f32_e32 v82, 1.0, v221
	v_cndmask_b32_e64 v82, v221, v82, s[46:47]
	s_waitcnt vmcnt(8)
	v_cndmask_b32_e64 v84, v153, v222, s[46:47]
	v_mul_f32_e32 v82, v82, v83
	v_mul_f32_e32 v83, v213, v16
	v_mul_f32_e32 v16, v84, v16
	v_max_f32_e32 v16, 0x14461206, v16
	v_cvt_pk_bf16_f32 v83, v83, s0
	v_rcp_f32_e32 v84, v16
	ds_write_b16 v107, v83 offset:1632
	v_cvt_pk_bf16_f32 v83, v82, s0
	ds_write_b16 v107, v83 offset:3808
	v_sub_f32_e32 v83, 1.0, v222
	v_cndmask_b32_e64 v83, v222, v83, s[46:47]
	s_waitcnt vmcnt(5)
; __device__ __forceinline__ bfu f2bf_hw(float x) { return (bfu)(pack2(x, x) & 0xffffu); }
; __device__ __forceinline__ void gla_pass3(const Ctx& cx, const Params& p, int l, int item, float* ldsf, int lane) {
;     ...
;           Qs[i * 68 + lane] = f2bf_hw(q * e);
;           Ks[i * 68 + lane] = f2bf_hw(kt[i]);
;         }
;         const float gdec = e;
;         gs[lane] = gdec;
; #pragma unroll
;         for (int q = 0; q < 4; ++q) {
;           u32x2 kk, vv;
;           kk.x = pack2(kt[4 * q] * gdec, kt[4 * q + 1] * gdec); kk.y = pack2(kt[4 * q + 2] * gdec, kt[4 * q + 3] * gdec);
;           vv.x = pack2(r2[4 * q], r2[4 * q + 1]); vv.y = pack2(r2[4 * q + 2], r2[4 * q + 3]);
;           *reinterpret_cast<u32x2*>(KTs + lane * 20 + 4 * q) = kk;
;           *reinterpret_cast<u32x2*>(VTs + lane * 20 + 4 * q) = vv;
;         }
;       }
;       wave_fence();
;       if (sub < 3) {
; #pragma unroll
;         for (int i = 0; i < 16; ++i) {
;           int s = (sub + 1) * 16 + i;
;           int tok = dir ? 63 - s : s;
;           const float* zr = z + (size_t)(rowbase + tok) * INW;
;           r0[i] = zr[cfoff + hc];
;           r1[i] = zr[cqoff + hc];
;           r2[i] = zr[cvoff + hc];
;         }
	v_cndmask_b32_e64 v85, v153, v226, s[46:47]
	v_mul_f32_e32 v83, v83, v84
	v_mul_f32_e32 v84, v217, v16
	v_mul_f32_e32 v16, v85, v16
	v_max_f32_e32 v16, 0x14461206, v16
	v_cvt_pk_bf16_f32 v84, v84, s0
	v_rcp_f32_e32 v85, v16
	ds_write_b16 v107, v84 offset:1768
	v_cvt_pk_bf16_f32 v84, v83, s0
	ds_write_b16 v107, v84 offset:3944
	v_sub_f32_e32 v84, 1.0, v226
	v_cndmask_b32_e64 v84, v226, v84, s[46:47]
	s_waitcnt vmcnt(2)
	v_cndmask_b32_e64 v86, v153, v227, s[46:47]
	v_mul_f32_e32 v84, v84, v85
	v_mul_f32_e32 v85, v218, v16
	v_mul_f32_e32 v16, v86, v16
	v_max_f32_e32 v86, 0x14461206, v16
	v_cvt_pk_bf16_f32 v85, v85, s0
	v_rcp_f32_e32 v16, v86
	ds_write_b16 v107, v85 offset:1904
	v_cvt_pk_bf16_f32 v85, v84, s0
	ds_write_b16 v107, v85 offset:4080
	v_sub_f32_e32 v85, 1.0, v227
	v_cndmask_b32_e64 v85, v227, v85, s[46:47]
	v_mul_f32_e32 v85, v85, v16
	s_waitcnt vmcnt(1)
	v_mul_f32_e32 v16, v219, v86
	v_cvt_pk_bf16_f32 v16, v16, s0
	ds_write_b16 v107, v16 offset:2040
	v_cvt_pk_bf16_f32 v16, v85, s0
	ds_write_b16 v107, v16 offset:4216
	ds_write_b32 v138, v86 offset:9472
	v_mul_f32_e32 v16, v17, v86
	v_mul_f32_e32 v17, v19, v86
	v_mul_f32_e32 v74, v74, v86
	v_mul_f32_e32 v75, v75, v86
	v_cvt_pk_bf16_f32 v16, v16, v17
	v_mul_f32_e32 v17, v72, v86
	v_mul_f32_e32 v19, v73, v86
	v_cvt_pk_bf16_f32 v74, v74, v75
	v_mul_f32_e32 v75, v76, v86
	v_mul_f32_e32 v76, v77, v86
	v_cvt_pk_bf16_f32 v17, v17, v19
	v_add_u32_e32 v19, 0x1100, v139
	v_cvt_pk_bf16_f32 v75, v75, v76
	v_cvt_pk_bf16_f32 v72, v123, v156
	v_cvt_pk_bf16_f32 v73, v161, v162
	v_add_u32_e32 v87, 0x1b00, v139
	v_cvt_pk_bf16_f32 v76, v163, v170
	v_cvt_pk_bf16_f32 v77, v171, v172
	ds_write2_b64 v19, v[16:17], v[74:75] offset1:1
	ds_write2_b64 v87, v[72:73], v[76:77] offset1:1
	v_mul_f32_e32 v16, v78, v86
	v_mul_f32_e32 v17, v79, v86
	v_mul_f32_e32 v74, v82, v86
	v_mul_f32_e32 v75, v83, v86
	v_cvt_pk_bf16_f32 v16, v16, v17
	v_mul_f32_e32 v17, v80, v86
	v_mul_f32_e32 v19, v81, v86
	v_cvt_pk_bf16_f32 v74, v74, v75
	v_mul_f32_e32 v75, v86, v84
	v_mul_f32_e32 v76, v86, v85
	v_cvt_pk_bf16_f32 v17, v17, v19
	v_cvt_pk_bf16_f32 v72, v207, v208
	v_cvt_pk_bf16_f32 v73, v214, v215
	v_add_u32_e32 v19, 0x1110, v139
	v_add_u32_e32 v78, 0x1b10, v139
	v_cvt_pk_bf16_f32 v75, v75, v76
	v_cvt_pk_bf16_f32 v76, v216, v223
	s_waitcnt vmcnt(0)
	v_cvt_pk_bf16_f32 v77, v224, v225
	s_cmp_lg_u32 s10, 48
	s_mov_b64 s[2:3], -1
	ds_write2_b64 v19, v[16:17], v[74:75] offset1:1
	ds_write2_b64 v78, v[72:73], v[76:77] offset1:1
	s_cbranch_scc0 .LBB0_132
	s_add_i32 s7, s10, 16
	s_add_i32 s11, s6, 15
	s_and_b64 s[2:3], s[0:1], exec
	s_cselect_b32 s2, s7, s11
	v_add_u32_e32 v19, s2, v147
	v_mov_b64_e32 v[16:17], s[22:23]
	v_mad_i64_i32 v[72:73], s[2:3], v19, s54, v[16:17]
	v_mov_b32_e32 v135, v18
	s_add_i32 s11, s10, 17
	s_add_i32 s20, s6, 14
	v_lshl_add_u64 v[74:75], v[72:73], 0, v[134:135]
	v_mov_b32_e32 v131, v18
	v_mov_b32_e32 v133, v18
	s_and_b64 s[2:3], s[0:1], exec
	global_load_dword v19, v[74:75], off nt
	v_lshl_add_u64 v[74:75], v[72:73], 0, v[130:131]
	v_lshl_add_u64 v[72:73], v[72:73], 0, v[132:133]
	s_cselect_b32 s2, s11, s20
	global_load_dword v75, v[74:75], off nt
	s_add_i32 s11, s10, 18
	global_load_dword v72, v[72:73], off nt
	v_add_u32_e32 v73, s2, v147
	v_mad_i64_i32 v[78:79], s[2:3], v73, s54, v[16:17]
	s_add_i32 s20, s6, 13
	v_lshl_add_u64 v[76:77], v[78:79], 0, v[134:135]
	s_and_b64 s[2:3], s[0:1], exec
	global_load_dword v73, v[76:77], off nt
	v_lshl_add_u64 v[76:77], v[78:79], 0, v[130:131]
	v_lshl_add_u64 v[78:79], v[78:79], 0, v[132:133]
	s_cselect_b32 s2, s11, s20
	global_load_dword v77, v[76:77], off nt
	s_add_i32 s11, s10, 19
	global_load_dword v74, v[78:79], off nt
	v_add_u32_e32 v76, s2, v147
	v_mad_i64_i32 v[78:79], s[2:3], v76, s54, v[16:17]
	s_add_i32 s20, s6, 12
	v_lshl_add_u64 v[80:81], v[78:79], 0, v[134:135]
	s_and_b64 s[2:3], s[0:1], exec
	global_load_dword v76, v[80:81], off nt
	v_lshl_add_u64 v[80:81], v[78:79], 0, v[130:131]
	v_lshl_add_u64 v[78:79], v[78:79], 0, v[132:133]
	s_cselect_b32 s2, s11, s20
	global_load_dword v82, v[80:81], off nt
	s_add_i32 s11, s10, 20
	global_load_dword v79, v[78:79], off nt
	v_add_u32_e32 v78, s2, v147
	v_mad_i64_i32 v[80:81], s[2:3], v78, s54, v[16:17]
	s_add_i32 s20, s6, 11
	v_lshl_add_u64 v[84:85], v[80:81], 0, v[134:135]
	s_and_b64 s[2:3], s[0:1], exec
	global_load_dword v78, v[84:85], off nt
	v_lshl_add_u64 v[84:85], v[80:81], 0, v[130:131]
	v_lshl_add_u64 v[80:81], v[80:81], 0, v[132:133]
	s_cselect_b32 s2, s11, s20
	global_load_dword v84, v[84:85], off nt
	s_add_i32 s11, s10, 21
	global_load_dword v81, v[80:81], off nt
	v_add_u32_e32 v80, s2, v147
	s_add_i32 s20, s6, 10
	v_mad_i64_i32 v[88:89], s[2:3], v80, s54, v[16:17]
	s_and_b64 s[2:3], s[0:1], exec
	v_lshl_add_u64 v[86:87], v[88:89], 0, v[134:135]
	s_cselect_b32 s2, s11, s20
	global_load_dword v80, v[86:87], off nt
	v_lshl_add_u64 v[86:87], v[88:89], 0, v[130:131]
	v_lshl_add_u64 v[88:89], v[88:89], 0, v[132:133]
	v_add_u32_e32 v85, s2, v147
	s_add_i32 s11, s10, 22
	s_add_i32 s20, s6, 9
	global_load_dword v86, v[86:87], off nt
	s_and_b64 s[2:3], s[0:1], exec
; __device__ __forceinline__ void gla_pass3(const Ctx& cx, const Params& p, int l, int item, float* ldsf, int lane) {
;     ...
;       if (sub < 3) {
; #pragma unroll
;         for (int i = 0; i < 16; ++i) {
;           int s = (sub + 1) * 16 + i;
;           int tok = dir ? 63 - s : s;
;           const float* zr = z + (size_t)(rowbase + tok) * INW;
;           r0[i] = zr[cfoff + hc];
;           r1[i] = zr[cqoff + hc];
;           r2[i] = zr[cvoff + hc];
;         }
;       }
	global_load_dword v83, v[88:89], off nt
	v_mad_i64_i32 v[88:89], s[2:3], v85, s54, v[16:17]
	s_cselect_b32 s2, s11, s20
	s_nop 0
	v_add_u32_e32 v87, s2, v147
	v_mad_i64_i32 v[94:95], s[2:3], v87, s54, v[16:17]
	s_add_i32 s11, s10, 23
	s_add_i32 s20, s6, 8
	v_lshl_add_u64 v[90:91], v[88:89], 0, v[134:135]
	v_lshl_add_u64 v[92:93], v[94:95], 0, v[134:135]
	s_and_b64 s[2:3], s[0:1], exec
	global_load_dword v85, v[90:91], off nt
	global_load_dword v87, v[92:93], off nt
	v_lshl_add_u64 v[90:91], v[88:89], 0, v[130:131]
	v_lshl_add_u64 v[88:89], v[88:89], 0, v[132:133]
	v_lshl_add_u64 v[92:93], v[94:95], 0, v[130:131]
	s_cselect_b32 s2, s11, s20
	global_load_dword v91, v[90:91], off nt
	v_lshl_add_u64 v[94:95], v[94:95], 0, v[132:133]
	global_load_dword v93, v[92:93], off nt
	s_add_i32 s11, s10, 24
	global_load_dword v88, v[88:89], off nt
	v_add_u32_e32 v89, s2, v147
	s_add_i32 s20, s6, 7
	global_load_dword v90, v[94:95], off nt
	v_mad_i64_i32 v[94:95], s[2:3], v89, s54, v[16:17]
	s_and_b64 s[2:3], s[0:1], exec
	s_cselect_b32 s2, s11, s20
	v_add_u32_e32 v92, s2, v147
	v_mad_i64_i32 v[98:99], s[2:3], v92, s54, v[16:17]
	v_lshl_add_u64 v[100:101], v[98:99], 0, v[134:135]
	s_add_i32 s11, s10, 25
	s_add_i32 s20, s6, 6
	v_lshl_add_u64 v[96:97], v[94:95], 0, v[134:135]
	global_load_dword v92, v[100:101], off nt
	v_lshl_add_u64 v[100:101], v[98:99], 0, v[130:131]
	v_lshl_add_u64 v[98:99], v[98:99], 0, v[132:133]
	s_and_b64 s[2:3], s[0:1], exec
	global_load_dword v89, v[96:97], off nt
	s_cselect_b32 s2, s11, s20
	global_load_dword v98, v[98:99], off nt
	v_lshl_add_u64 v[96:97], v[94:95], 0, v[130:131]
	v_lshl_add_u64 v[94:95], v[94:95], 0, v[132:133]
	global_load_dword v96, v[96:97], off nt
	s_add_i32 s11, s10, 26
	global_load_dword v100, v[100:101], off nt
	s_add_i32 s20, s6, 5
	global_load_dword v95, v[94:95], off nt
	v_add_u32_e32 v94, s2, v147
	v_mad_i64_i32 v[136:137], s[2:3], v94, s54, v[16:17]
	s_and_b64 s[2:3], s[0:1], exec
	v_lshl_add_u64 v[102:103], v[136:137], 0, v[134:135]
	s_cselect_b32 s2, s11, s20
	global_load_dword v94, v[102:103], off nt
	v_lshl_add_u64 v[102:103], v[136:137], 0, v[130:131]
	v_lshl_add_u64 v[136:137], v[136:137], 0, v[132:133]
	v_add_u32_e32 v97, s2, v147
	s_add_i32 s11, s10, 27
	s_add_i32 s20, s6, 4
	global_load_dword v103, v[102:103], off nt
	s_and_b64 s[2:3], s[0:1], exec
	global_load_dword v99, v[136:137], off nt
	v_mad_i64_i32 v[136:137], s[2:3], v97, s54, v[16:17]
	v_lshl_add_u64 v[148:149], v[136:137], 0, v[134:135]
	s_cselect_b32 s2, s11, s20
	global_load_dword v97, v[148:149], off nt
	v_lshl_add_u64 v[148:149], v[136:137], 0, v[130:131]
	v_lshl_add_u64 v[136:137], v[136:137], 0, v[132:133]
	v_add_u32_e32 v101, s2, v147
	s_add_i32 s11, s10, 28
	s_add_i32 s20, s6, 3
	global_load_dword v229, v[148:149], off nt
	s_and_b64 s[2:3], s[0:1], exec
	global_load_dword v136, v[136:137], off nt
	v_mad_i64_i32 v[148:149], s[2:3], v101, s54, v[16:17]
	v_lshl_add_u64 v[150:151], v[148:149], 0, v[134:135]
	s_cselect_b32 s2, s11, s20
	global_load_dword v101, v[150:151], off nt
	v_lshl_add_u64 v[150:151], v[148:149], 0, v[130:131]
	v_lshl_add_u64 v[148:149], v[148:149], 0, v[132:133]
	v_add_u32_e32 v102, s2, v147
	global_load_dword v232, v[150:151], off nt
	global_load_dword v137, v[148:149], off nt
	v_mad_i64_i32 v[148:149], s[2:3], v102, s54, v[16:17]
	s_add_i32 s11, s10, 29
	s_add_i32 s20, s6, 2
	v_lshl_add_u64 v[150:151], v[148:149], 0, v[134:135]
	s_and_b64 s[2:3], s[0:1], exec
	global_load_dword v102, v[150:151], off nt
	v_lshl_add_u64 v[150:151], v[148:149], 0, v[130:131]
	v_lshl_add_u64 v[148:149], v[148:149], 0, v[132:133]
	s_cselect_b32 s2, s11, s20
	global_load_dword v233, v[150:151], off nt
	global_load_dword v231, v[148:149], off nt
	v_add_u32_e32 v148, s2, v147
	v_mad_i64_i32 v[148:149], s[2:3], v148, s54, v[16:17]
	s_add_i32 s11, s10, 30
	s_add_i32 s20, s6, 1
	v_lshl_add_u64 v[150:151], v[148:149], 0, v[134:135]
	s_and_b64 s[2:3], s[0:1], exec
	global_load_dword v228, v[150:151], off nt
	v_lshl_add_u64 v[150:151], v[148:149], 0, v[130:131]
	v_lshl_add_u64 v[148:149], v[148:149], 0, v[132:133]
	s_cselect_b32 s2, s11, s20
	global_load_dword v236, v[150:151], off nt
	global_load_dword v234, v[148:149], off nt
	v_add_u32_e32 v148, s2, v147
	v_mad_i64_i32 v[148:149], s[2:3], v148, s54, v[16:17]
	s_add_i32 s11, s10, 31
	v_lshl_add_u64 v[150:151], v[148:149], 0, v[134:135]
	s_and_b64 s[2:3], s[0:1], exec
	global_load_dword v230, v[150:151], off nt
	v_lshl_add_u64 v[150:151], v[148:149], 0, v[130:131]
	v_lshl_add_u64 v[148:149], v[148:149], 0, v[132:133]
	s_cselect_b32 s2, s11, s6
	global_load_dword v235, v[148:149], off nt
	v_add_u32_e32 v148, s2, v147
	v_mad_i64_i32 v[148:149], s[2:3], v148, s54, v[16:17]
	v_lshl_add_u64 v[16:17], v[148:149], 0, v[134:135]
	global_load_dword v237, v[150:151], off nt
	s_mov_b64 s[2:3], 0
	global_load_dword v16, v[16:17], off nt
	v_lshl_add_u64 v[150:151], v[148:149], 0, v[130:131]
	v_lshl_add_u64 v[148:149], v[148:149], 0, v[132:133]
	global_load_dword v131, v[150:151], off nt
	global_load_dword v17, v[148:149], off nt
